# K loops of G_WIN and G_UP restructured: every wave defers the second half of each K-step MFMA work past the next barrier (fragments stay in registers), so matrix work is available while the LDS reads
# speedup vs baseline: 1.0835x; 1.0228x over previous
.Lg2_a_item1:
	s_mul_i32 s11, s10, 0x2aab
	s_lshr_b32 s11, s11, 16
	s_mul_i32 s12, s11, 6
	s_sub_u32 s12, s10, s12
	s_mov_b32 s16, 0
	s_and_b32 s17, s14, 3
	s_mul_i32 s17, s17, 6
	s_add_u32 s12, s12, s17
	s_lshl_b32 s12, s12, 8
	s_add_u32 s12, s12, s16
	s_lshr_b32 s17, s14, 2
	s_mul_i32 s17, s17, 22
	s_lshl_b32 s11, s11, 1
	s_add_u32 s11, s11, s17
	s_lshl_b32 s16, s12, 11
	s_add_u32 s0, s24, s16
	s_addc_u32 s1, s25, 0
	s_lshl_b32 s16, s11, 18
	s_add_u32 s2, s40, s16
	s_addc_u32 s3, s41, 0
	s_mul_i32 s16, s12, 0x1600
	s_lshl_b32 s17, s11, 7
	s_add_u32 s16, s16, s17
	s_add_u32 s4, s26, s16
	s_addc_u32 s5, s27, 0
	s_add_u32 m0, s6, 0x0
	s_nop 0
	global_load_lds_dwordx4 v136, s[0:1]
	s_add_u32 m0, s6, 0x2000
	s_nop 0
	global_load_lds_dwordx4 v137, s[0:1]
	s_add_u32 m0, s6, 0x4000
	s_nop 0
	global_load_lds_dwordx4 v136, s[2:3]
	s_add_u32 m0, s6, 0x6000
	s_nop 0
	global_load_lds_dwordx4 v137, s[2:3]
	s_add_u32 s0, s0, 64
	s_addc_u32 s1, s1, 0
	s_add_u32 s2, s2, 64
	s_addc_u32 s3, s3, 0
	s_add_u32 m0, s6, 0x8000
	s_nop 0
	global_load_lds_dwordx4 v136, s[0:1]
	s_add_u32 m0, s6, 0xa000
	s_nop 0
	global_load_lds_dwordx4 v137, s[0:1]
	s_add_u32 m0, s6, 0xc000
	s_nop 0
	global_load_lds_dwordx4 v136, s[2:3]
	s_add_u32 m0, s6, 0xe000
	s_nop 0
	global_load_lds_dwordx4 v137, s[2:3]
	s_add_u32 s0, s0, 64
	s_addc_u32 s1, s1, 0
	s_add_u32 s2, s2, 64
	s_addc_u32 s3, s3, 0
	s_add_u32 m0, s6, 0x10000
	s_nop 0
	global_load_lds_dwordx4 v136, s[0:1]
	s_add_u32 m0, s6, 0x12000
	s_nop 0
	global_load_lds_dwordx4 v137, s[0:1]
	s_add_u32 m0, s6, 0x14000
	s_nop 0
	global_load_lds_dwordx4 v136, s[2:3]
	s_add_u32 m0, s6, 0x16000
	s_nop 0
	global_load_lds_dwordx4 v137, s[2:3]
	s_add_u32 s0, s0, 64
	s_addc_u32 s1, s1, 0
	s_add_u32 s2, s2, 64
	s_addc_u32 s3, s3, 0
	v_mov_b32_e32 v2, 0
	v_mov_b32_e32 v3, 0
	v_mov_b32_e32 v4, 0
	v_mov_b32_e32 v5, 0
	v_mov_b32_e32 v6, 0
	v_mov_b32_e32 v7, 0
	v_mov_b32_e32 v8, 0
	v_mov_b32_e32 v9, 0
	v_mov_b32_e32 v10, 0
	v_mov_b32_e32 v11, 0
	v_mov_b32_e32 v12, 0
	v_mov_b32_e32 v13, 0
	v_mov_b32_e32 v14, 0
	v_mov_b32_e32 v15, 0
	v_mov_b32_e32 v16, 0
	v_mov_b32_e32 v17, 0
	v_mov_b32_e32 v18, 0
	v_mov_b32_e32 v19, 0
	v_mov_b32_e32 v20, 0
	v_mov_b32_e32 v21, 0
	v_mov_b32_e32 v22, 0
	v_mov_b32_e32 v23, 0
	v_mov_b32_e32 v24, 0
	v_mov_b32_e32 v25, 0
	v_mov_b32_e32 v26, 0
	v_mov_b32_e32 v27, 0
	v_mov_b32_e32 v28, 0
	v_mov_b32_e32 v29, 0
	v_mov_b32_e32 v30, 0
	v_mov_b32_e32 v31, 0
	v_mov_b32_e32 v32, 0
	v_mov_b32_e32 v33, 0
	v_mov_b32_e32 v34, 0
	v_mov_b32_e32 v35, 0
	v_mov_b32_e32 v36, 0
	v_mov_b32_e32 v37, 0
	v_mov_b32_e32 v38, 0
	v_mov_b32_e32 v39, 0
	v_mov_b32_e32 v40, 0
	v_mov_b32_e32 v41, 0
	v_mov_b32_e32 v42, 0
	v_mov_b32_e32 v43, 0
	v_mov_b32_e32 v44, 0
	v_mov_b32_e32 v45, 0
	v_mov_b32_e32 v46, 0
	v_mov_b32_e32 v47, 0
	v_mov_b32_e32 v48, 0
	v_mov_b32_e32 v49, 0
	v_mov_b32_e32 v50, 0
	v_mov_b32_e32 v51, 0
	v_mov_b32_e32 v52, 0
	v_mov_b32_e32 v53, 0
	v_mov_b32_e32 v54, 0
	v_mov_b32_e32 v55, 0
	v_mov_b32_e32 v56, 0
	v_mov_b32_e32 v57, 0
	v_mov_b32_e32 v58, 0
	v_mov_b32_e32 v59, 0
	v_mov_b32_e32 v60, 0
	v_mov_b32_e32 v61, 0
	v_mov_b32_e32 v62, 0
	v_mov_b32_e32 v63, 0
	v_mov_b32_e32 v64, 0
	v_mov_b32_e32 v65, 0
	v_mov_b32_e32 v66, 0
	v_mov_b32_e32 v67, 0
	v_mov_b32_e32 v68, 0
	v_mov_b32_e32 v69, 0
	v_mov_b32_e32 v70, 0
	v_mov_b32_e32 v71, 0
	v_mov_b32_e32 v72, 0
	v_mov_b32_e32 v73, 0
	v_mov_b32_e32 v74, 0
	v_mov_b32_e32 v75, 0
	v_mov_b32_e32 v76, 0
	v_mov_b32_e32 v77, 0
	v_mov_b32_e32 v78, 0
	v_mov_b32_e32 v79, 0
	v_mov_b32_e32 v80, 0
	v_mov_b32_e32 v81, 0
	v_mov_b32_e32 v82, 0
	v_mov_b32_e32 v83, 0
	v_mov_b32_e32 v84, 0
	v_mov_b32_e32 v85, 0
	v_mov_b32_e32 v86, 0
	v_mov_b32_e32 v87, 0
	v_mov_b32_e32 v88, 0
	v_mov_b32_e32 v89, 0
	v_mov_b32_e32 v90, 0
	v_mov_b32_e32 v91, 0
	v_mov_b32_e32 v92, 0
	v_mov_b32_e32 v93, 0
	v_mov_b32_e32 v94, 0
	v_mov_b32_e32 v95, 0
	v_mov_b32_e32 v96, 0
	v_mov_b32_e32 v97, 0
	v_mov_b32_e32 v98, 0
	v_mov_b32_e32 v99, 0
	v_mov_b32_e32 v100, 0
	v_mov_b32_e32 v101, 0
	v_mov_b32_e32 v102, 0
	v_mov_b32_e32 v103, 0
	v_mov_b32_e32 v104, 0
	v_mov_b32_e32 v105, 0
	v_mov_b32_e32 v106, 0
	v_mov_b32_e32 v107, 0
	v_mov_b32_e32 v108, 0
	v_mov_b32_e32 v109, 0
	v_mov_b32_e32 v110, 0
	v_mov_b32_e32 v111, 0
	v_mov_b32_e32 v112, 0
	v_mov_b32_e32 v113, 0
	v_mov_b32_e32 v114, 0
	v_mov_b32_e32 v115, 0
	v_mov_b32_e32 v116, 0
	v_mov_b32_e32 v117, 0
	v_mov_b32_e32 v118, 0
	v_mov_b32_e32 v119, 0
	v_mov_b32_e32 v120, 0
	v_mov_b32_e32 v121, 0
	v_mov_b32_e32 v122, 0
	v_mov_b32_e32 v123, 0
	v_mov_b32_e32 v124, 0
	v_mov_b32_e32 v125, 0
	v_mov_b32_e32 v126, 0
	v_mov_b32_e32 v127, 0
	v_mov_b32_e32 v128, 0
	v_mov_b32_e32 v129, 0
.Lg2_a_grpB2:
	v_mov_b32_e32 v178, 0
	v_mov_b32_e32 v179, 0
	v_mov_b32_e32 v180, 0
	v_mov_b32_e32 v181, 0
	v_mov_b32_e32 v182, 0
	v_mov_b32_e32 v183, 0
	v_mov_b32_e32 v184, 0
	v_mov_b32_e32 v185, 0
	v_mov_b32_e32 v186, 0
	v_mov_b32_e32 v187, 0
	v_mov_b32_e32 v188, 0
	v_mov_b32_e32 v189, 0
	v_mov_b32_e32 v190, 0
	v_mov_b32_e32 v191, 0
	v_mov_b32_e32 v192, 0
	v_mov_b32_e32 v193, 0
	v_mov_b32_e32 v218, 0
	v_mov_b32_e32 v219, 0
	v_mov_b32_e32 v220, 0
	v_mov_b32_e32 v221, 0
	v_mov_b32_e32 v222, 0
	v_mov_b32_e32 v223, 0
	v_mov_b32_e32 v224, 0
	v_mov_b32_e32 v225, 0
	v_mov_b32_e32 v226, 0
	v_mov_b32_e32 v227, 0
	v_mov_b32_e32 v228, 0
	v_mov_b32_e32 v229, 0
	v_mov_b32_e32 v230, 0
	v_mov_b32_e32 v231, 0
	v_mov_b32_e32 v232, 0
	v_mov_b32_e32 v233, 0
	s_mov_b32 s7, 7

.Lg2_a_kdone3:
	s_nop 7
	s_nop 1
	v_mov_b32_e32 v176, v138
	v_mul_f32_e32 v162, 0xbfb8aa3b, v2
	v_mul_f32_e32 v163, 0xbfb8aa3b, v3
	v_mul_f32_e32 v164, 0xbfb8aa3b, v4
	v_mul_f32_e32 v165, 0xbfb8aa3b, v5
	v_exp_f32_e32 v162, v162
	v_exp_f32_e32 v163, v163
	v_exp_f32_e32 v164, v164
	v_exp_f32_e32 v165, v165
	v_add_f32_e32 v162, 1.0, v162
	v_add_f32_e32 v163, 1.0, v163
	v_add_f32_e32 v164, 1.0, v164
	v_add_f32_e32 v165, 1.0, v165
	v_rcp_f32_e32 v162, v162
	v_rcp_f32_e32 v163, v163
	v_rcp_f32_e32 v164, v164
	v_rcp_f32_e32 v165, v165
	v_mul_f32_e32 v162, v2, v162
	v_mul_f32_e32 v163, v3, v163
	v_mul_f32_e32 v164, v4, v164
	v_mul_f32_e32 v165, v5, v165
	v_mul_f32_e32 v162, v10, v162
	v_mul_f32_e32 v163, v11, v163
	v_mul_f32_e32 v164, v12, v164
	v_mul_f32_e32 v165, v13, v165
	v_cvt_pk_bf16_f32 v168, v162, v163
	v_cvt_pk_bf16_f32 v169, v164, v165
	v_mul_f32_e32 v162, 0xbfb8aa3b, v6
	v_mul_f32_e32 v163, 0xbfb8aa3b, v7
	v_mul_f32_e32 v164, 0xbfb8aa3b, v8
	v_mul_f32_e32 v165, 0xbfb8aa3b, v9
	v_exp_f32_e32 v162, v162
	v_exp_f32_e32 v163, v163
	v_exp_f32_e32 v164, v164
	v_exp_f32_e32 v165, v165
	v_add_f32_e32 v162, 1.0, v162
	v_add_f32_e32 v163, 1.0, v163
	v_add_f32_e32 v164, 1.0, v164
	v_add_f32_e32 v165, 1.0, v165
	v_rcp_f32_e32 v162, v162
	v_rcp_f32_e32 v163, v163
	v_rcp_f32_e32 v164, v164
	v_rcp_f32_e32 v165, v165
	v_mul_f32_e32 v162, v6, v162
	v_mul_f32_e32 v163, v7, v163
	v_mul_f32_e32 v164, v8, v164
	v_mul_f32_e32 v165, v9, v165
	v_mul_f32_e32 v162, v14, v162
	v_mul_f32_e32 v163, v15, v163
	v_mul_f32_e32 v164, v16, v164
	v_mul_f32_e32 v165, v17, v165
	v_cvt_pk_bf16_f32 v170, v162, v163
	v_cvt_pk_bf16_f32 v171, v164, v165
	s_nop 1
	v_permlane16_swap_b32_e32 v168, v170
	v_permlane16_swap_b32_e32 v169, v171
	global_store_dwordx4 v176, v[168:171], s[4:5] offset:0 sc1
	v_mul_f32_e32 v162, 0xbfb8aa3b, v66
	v_mul_f32_e32 v163, 0xbfb8aa3b, v67
	v_mul_f32_e32 v164, 0xbfb8aa3b, v68
	v_mul_f32_e32 v165, 0xbfb8aa3b, v69
	v_exp_f32_e32 v162, v162
	v_exp_f32_e32 v163, v163
	v_exp_f32_e32 v164, v164
	v_exp_f32_e32 v165, v165
	v_add_f32_e32 v162, 1.0, v162
	v_add_f32_e32 v163, 1.0, v163
	v_add_f32_e32 v164, 1.0, v164
	v_add_f32_e32 v165, 1.0, v165
	v_rcp_f32_e32 v162, v162
	v_rcp_f32_e32 v163, v163
	v_rcp_f32_e32 v164, v164
	v_rcp_f32_e32 v165, v165
	v_mul_f32_e32 v162, v66, v162
	v_mul_f32_e32 v163, v67, v163
	v_mul_f32_e32 v164, v68, v164
	v_mul_f32_e32 v165, v69, v165
	v_mul_f32_e32 v162, v74, v162
	v_mul_f32_e32 v163, v75, v163
	v_mul_f32_e32 v164, v76, v164
	v_mul_f32_e32 v165, v77, v165
	v_cvt_pk_bf16_f32 v172, v162, v163
	v_cvt_pk_bf16_f32 v173, v164, v165
	v_mul_f32_e32 v162, 0xbfb8aa3b, v70
	v_mul_f32_e32 v163, 0xbfb8aa3b, v71
	v_mul_f32_e32 v164, 0xbfb8aa3b, v72
	v_mul_f32_e32 v165, 0xbfb8aa3b, v73
	v_exp_f32_e32 v162, v162
	v_exp_f32_e32 v163, v163
	v_exp_f32_e32 v164, v164
	v_exp_f32_e32 v165, v165
	v_add_f32_e32 v162, 1.0, v162
	v_add_f32_e32 v163, 1.0, v163
	v_add_f32_e32 v164, 1.0, v164
	v_add_f32_e32 v165, 1.0, v165
	v_rcp_f32_e32 v162, v162
	v_rcp_f32_e32 v163, v163
	v_rcp_f32_e32 v164, v164
	v_rcp_f32_e32 v165, v165
	v_mul_f32_e32 v162, v70, v162
	v_mul_f32_e32 v163, v71, v163
	v_mul_f32_e32 v164, v72, v164
	v_mul_f32_e32 v165, v73, v165
	v_mul_f32_e32 v162, v78, v162
	v_mul_f32_e32 v163, v79, v163
	v_mul_f32_e32 v164, v80, v164
	v_mul_f32_e32 v165, v81, v165
	v_cvt_pk_bf16_f32 v174, v162, v163
	v_cvt_pk_bf16_f32 v175, v164, v165
	s_nop 1
	v_permlane16_swap_b32_e32 v172, v174
	v_permlane16_swap_b32_e32 v173, v175
	global_store_dwordx4 v176, v[172:175], s[4:5] offset:128 sc1
	v_add_u32_e32 v176, 0x16000, v176
	v_mul_f32_e32 v162, 0xbfb8aa3b, v18
	v_mul_f32_e32 v163, 0xbfb8aa3b, v19
	v_mul_f32_e32 v164, 0xbfb8aa3b, v20
	v_mul_f32_e32 v165, 0xbfb8aa3b, v21
	v_exp_f32_e32 v162, v162
	v_exp_f32_e32 v163, v163
	v_exp_f32_e32 v164, v164
	v_exp_f32_e32 v165, v165
	v_add_f32_e32 v162, 1.0, v162
	v_add_f32_e32 v163, 1.0, v163
	v_add_f32_e32 v164, 1.0, v164
	v_add_f32_e32 v165, 1.0, v165
	v_rcp_f32_e32 v162, v162
	v_rcp_f32_e32 v163, v163
	v_rcp_f32_e32 v164, v164
	v_rcp_f32_e32 v165, v165
	v_mul_f32_e32 v162, v18, v162
	v_mul_f32_e32 v163, v19, v163
	v_mul_f32_e32 v164, v20, v164
	v_mul_f32_e32 v165, v21, v165
	v_mul_f32_e32 v162, v26, v162
	v_mul_f32_e32 v163, v27, v163
	v_mul_f32_e32 v164, v28, v164
	v_mul_f32_e32 v165, v29, v165
	v_cvt_pk_bf16_f32 v168, v162, v163
	v_cvt_pk_bf16_f32 v169, v164, v165
	v_mul_f32_e32 v162, 0xbfb8aa3b, v22
	v_mul_f32_e32 v163, 0xbfb8aa3b, v23
	v_mul_f32_e32 v164, 0xbfb8aa3b, v24
	v_mul_f32_e32 v165, 0xbfb8aa3b, v25
	v_exp_f32_e32 v162, v162
	v_exp_f32_e32 v163, v163
	v_exp_f32_e32 v164, v164
	v_exp_f32_e32 v165, v165
	v_add_f32_e32 v162, 1.0, v162
	v_add_f32_e32 v163, 1.0, v163
	v_add_f32_e32 v164, 1.0, v164
	v_add_f32_e32 v165, 1.0, v165
	v_rcp_f32_e32 v162, v162
	v_rcp_f32_e32 v163, v163
	v_rcp_f32_e32 v164, v164
	v_rcp_f32_e32 v165, v165
	v_mul_f32_e32 v162, v22, v162
	v_mul_f32_e32 v163, v23, v163
	v_mul_f32_e32 v164, v24, v164
	v_mul_f32_e32 v165, v25, v165
	v_mul_f32_e32 v162, v30, v162
	v_mul_f32_e32 v163, v31, v163
	v_mul_f32_e32 v164, v32, v164
	v_mul_f32_e32 v165, v33, v165
	v_cvt_pk_bf16_f32 v170, v162, v163
	v_cvt_pk_bf16_f32 v171, v164, v165
	s_nop 1
	v_permlane16_swap_b32_e32 v168, v170
	v_permlane16_swap_b32_e32 v169, v171
	global_store_dwordx4 v176, v[168:171], s[4:5] offset:0 sc1
	v_mul_f32_e32 v162, 0xbfb8aa3b, v82
	v_mul_f32_e32 v163, 0xbfb8aa3b, v83
	v_mul_f32_e32 v164, 0xbfb8aa3b, v84
	v_mul_f32_e32 v165, 0xbfb8aa3b, v85
	v_exp_f32_e32 v162, v162
	v_exp_f32_e32 v163, v163
	v_exp_f32_e32 v164, v164
	v_exp_f32_e32 v165, v165
	v_add_f32_e32 v162, 1.0, v162
	v_add_f32_e32 v163, 1.0, v163
	v_add_f32_e32 v164, 1.0, v164
	v_add_f32_e32 v165, 1.0, v165
	v_rcp_f32_e32 v162, v162
	v_rcp_f32_e32 v163, v163
	v_rcp_f32_e32 v164, v164
	v_rcp_f32_e32 v165, v165
	v_mul_f32_e32 v162, v82, v162
	v_mul_f32_e32 v163, v83, v163
	v_mul_f32_e32 v164, v84, v164
	v_mul_f32_e32 v165, v85, v165
	v_mul_f32_e32 v162, v90, v162
	v_mul_f32_e32 v163, v91, v163
	v_mul_f32_e32 v164, v92, v164
	v_mul_f32_e32 v165, v93, v165
	v_cvt_pk_bf16_f32 v172, v162, v163
	v_cvt_pk_bf16_f32 v173, v164, v165
	v_mul_f32_e32 v162, 0xbfb8aa3b, v86
	v_mul_f32_e32 v163, 0xbfb8aa3b, v87
	v_mul_f32_e32 v164, 0xbfb8aa3b, v88
	v_mul_f32_e32 v165, 0xbfb8aa3b, v89
	v_exp_f32_e32 v162, v162
	v_exp_f32_e32 v163, v163
	v_exp_f32_e32 v164, v164
	v_exp_f32_e32 v165, v165
	v_add_f32_e32 v162, 1.0, v162
	v_add_f32_e32 v163, 1.0, v163
	v_add_f32_e32 v164, 1.0, v164
	v_add_f32_e32 v165, 1.0, v165
	v_rcp_f32_e32 v162, v162
	v_rcp_f32_e32 v163, v163
	v_rcp_f32_e32 v164, v164
	v_rcp_f32_e32 v165, v165
	v_mul_f32_e32 v162, v86, v162
	v_mul_f32_e32 v163, v87, v163
	v_mul_f32_e32 v164, v88, v164
	v_mul_f32_e32 v165, v89, v165
	v_mul_f32_e32 v162, v94, v162
	v_mul_f32_e32 v163, v95, v163
	v_mul_f32_e32 v164, v96, v164
	v_mul_f32_e32 v165, v97, v165
	v_cvt_pk_bf16_f32 v174, v162, v163
	v_cvt_pk_bf16_f32 v175, v164, v165
	s_nop 1
	v_permlane16_swap_b32_e32 v172, v174
	v_permlane16_swap_b32_e32 v173, v175
	global_store_dwordx4 v176, v[172:175], s[4:5] offset:128 sc1
	v_add_u32_e32 v176, 0x16000, v176
	v_mul_f32_e32 v162, 0xbfb8aa3b, v34
	v_mul_f32_e32 v163, 0xbfb8aa3b, v35
	v_mul_f32_e32 v164, 0xbfb8aa3b, v36
	v_mul_f32_e32 v165, 0xbfb8aa3b, v37
	v_exp_f32_e32 v162, v162
	v_exp_f32_e32 v163, v163
	v_exp_f32_e32 v164, v164
	v_exp_f32_e32 v165, v165
	v_add_f32_e32 v162, 1.0, v162
	v_add_f32_e32 v163, 1.0, v163
	v_add_f32_e32 v164, 1.0, v164
	v_add_f32_e32 v165, 1.0, v165
	v_rcp_f32_e32 v162, v162
	v_rcp_f32_e32 v163, v163
	v_rcp_f32_e32 v164, v164
	v_rcp_f32_e32 v165, v165
	v_mul_f32_e32 v162, v34, v162
	v_mul_f32_e32 v163, v35, v163
	v_mul_f32_e32 v164, v36, v164
	v_mul_f32_e32 v165, v37, v165
	v_mul_f32_e32 v162, v42, v162
	v_mul_f32_e32 v163, v43, v163
	v_mul_f32_e32 v164, v44, v164
	v_mul_f32_e32 v165, v45, v165
	v_cvt_pk_bf16_f32 v168, v162, v163
	v_cvt_pk_bf16_f32 v169, v164, v165
	v_mul_f32_e32 v162, 0xbfb8aa3b, v38
	v_mul_f32_e32 v163, 0xbfb8aa3b, v39
	v_mul_f32_e32 v164, 0xbfb8aa3b, v40
	v_mul_f32_e32 v165, 0xbfb8aa3b, v41
	v_exp_f32_e32 v162, v162
	v_exp_f32_e32 v163, v163
	v_exp_f32_e32 v164, v164
	v_exp_f32_e32 v165, v165
	v_add_f32_e32 v162, 1.0, v162
	v_add_f32_e32 v163, 1.0, v163
	v_add_f32_e32 v164, 1.0, v164
	v_add_f32_e32 v165, 1.0, v165
	v_rcp_f32_e32 v162, v162
	v_rcp_f32_e32 v163, v163
	v_rcp_f32_e32 v164, v164
	v_rcp_f32_e32 v165, v165
	v_mul_f32_e32 v162, v38, v162
	v_mul_f32_e32 v163, v39, v163
	v_mul_f32_e32 v164, v40, v164
	v_mul_f32_e32 v165, v41, v165
	v_mul_f32_e32 v162, v46, v162
	v_mul_f32_e32 v163, v47, v163
	v_mul_f32_e32 v164, v48, v164
	v_mul_f32_e32 v165, v49, v165
	v_cvt_pk_bf16_f32 v170, v162, v163
	v_cvt_pk_bf16_f32 v171, v164, v165
	s_nop 1
	v_permlane16_swap_b32_e32 v168, v170
	v_permlane16_swap_b32_e32 v169, v171
	global_store_dwordx4 v176, v[168:171], s[4:5] offset:0 sc1
	v_mul_f32_e32 v162, 0xbfb8aa3b, v98
	v_mul_f32_e32 v163, 0xbfb8aa3b, v99
	v_mul_f32_e32 v164, 0xbfb8aa3b, v100
	v_mul_f32_e32 v165, 0xbfb8aa3b, v101
	v_exp_f32_e32 v162, v162
	v_exp_f32_e32 v163, v163
	v_exp_f32_e32 v164, v164
	v_exp_f32_e32 v165, v165
	v_add_f32_e32 v162, 1.0, v162
	v_add_f32_e32 v163, 1.0, v163
	v_add_f32_e32 v164, 1.0, v164
	v_add_f32_e32 v165, 1.0, v165
	v_rcp_f32_e32 v162, v162
	v_rcp_f32_e32 v163, v163
	v_rcp_f32_e32 v164, v164
	v_rcp_f32_e32 v165, v165
	v_mul_f32_e32 v162, v98, v162
	v_mul_f32_e32 v163, v99, v163
	v_mul_f32_e32 v164, v100, v164
	v_mul_f32_e32 v165, v101, v165
	v_mul_f32_e32 v162, v106, v162
	v_mul_f32_e32 v163, v107, v163
	v_mul_f32_e32 v164, v108, v164
	v_mul_f32_e32 v165, v109, v165
	v_cvt_pk_bf16_f32 v172, v162, v163
	v_cvt_pk_bf16_f32 v173, v164, v165
	v_mul_f32_e32 v162, 0xbfb8aa3b, v102
	v_mul_f32_e32 v163, 0xbfb8aa3b, v103
	v_mul_f32_e32 v164, 0xbfb8aa3b, v104
	v_mul_f32_e32 v165, 0xbfb8aa3b, v105
	v_exp_f32_e32 v162, v162
	v_exp_f32_e32 v163, v163
	v_exp_f32_e32 v164, v164
	v_exp_f32_e32 v165, v165
	v_add_f32_e32 v162, 1.0, v162
	v_add_f32_e32 v163, 1.0, v163
	v_add_f32_e32 v164, 1.0, v164
	v_add_f32_e32 v165, 1.0, v165
	v_rcp_f32_e32 v162, v162
	v_rcp_f32_e32 v163, v163
	v_rcp_f32_e32 v164, v164
	v_rcp_f32_e32 v165, v165
	v_mul_f32_e32 v162, v102, v162
	v_mul_f32_e32 v163, v103, v163
	v_mul_f32_e32 v164, v104, v164
	v_mul_f32_e32 v165, v105, v165
	v_mul_f32_e32 v162, v110, v162
	v_mul_f32_e32 v163, v111, v163
	v_mul_f32_e32 v164, v112, v164
	v_mul_f32_e32 v165, v113, v165
	v_cvt_pk_bf16_f32 v174, v162, v163
	v_cvt_pk_bf16_f32 v175, v164, v165
	s_nop 1
	v_permlane16_swap_b32_e32 v172, v174
	v_permlane16_swap_b32_e32 v173, v175
	global_store_dwordx4 v176, v[172:175], s[4:5] offset:128 sc1
	v_add_u32_e32 v176, 0x16000, v176
	v_mul_f32_e32 v162, 0xbfb8aa3b, v50
	v_mul_f32_e32 v163, 0xbfb8aa3b, v51
	v_mul_f32_e32 v164, 0xbfb8aa3b, v52
	v_mul_f32_e32 v165, 0xbfb8aa3b, v53
	v_exp_f32_e32 v162, v162
	v_exp_f32_e32 v163, v163
	v_exp_f32_e32 v164, v164
	v_exp_f32_e32 v165, v165
	v_add_f32_e32 v162, 1.0, v162
	v_add_f32_e32 v163, 1.0, v163
	v_add_f32_e32 v164, 1.0, v164
	v_add_f32_e32 v165, 1.0, v165
	v_rcp_f32_e32 v162, v162
	v_rcp_f32_e32 v163, v163
	v_rcp_f32_e32 v164, v164
	v_rcp_f32_e32 v165, v165
	v_mul_f32_e32 v162, v50, v162
	v_mul_f32_e32 v163, v51, v163
	v_mul_f32_e32 v164, v52, v164
	v_mul_f32_e32 v165, v53, v165
	v_mul_f32_e32 v162, v58, v162
	v_mul_f32_e32 v163, v59, v163
	v_mul_f32_e32 v164, v60, v164
	v_mul_f32_e32 v165, v61, v165
	v_cvt_pk_bf16_f32 v168, v162, v163
	v_cvt_pk_bf16_f32 v169, v164, v165
	v_mul_f32_e32 v162, 0xbfb8aa3b, v54
	v_mul_f32_e32 v163, 0xbfb8aa3b, v55
	v_mul_f32_e32 v164, 0xbfb8aa3b, v56
	v_mul_f32_e32 v165, 0xbfb8aa3b, v57
	v_exp_f32_e32 v162, v162
	v_exp_f32_e32 v163, v163
	v_exp_f32_e32 v164, v164
	v_exp_f32_e32 v165, v165
	v_add_f32_e32 v162, 1.0, v162
	v_add_f32_e32 v163, 1.0, v163
	v_add_f32_e32 v164, 1.0, v164
	v_add_f32_e32 v165, 1.0, v165
	v_rcp_f32_e32 v162, v162
	v_rcp_f32_e32 v163, v163
	v_rcp_f32_e32 v164, v164
	v_rcp_f32_e32 v165, v165
	v_mul_f32_e32 v162, v54, v162
	v_mul_f32_e32 v163, v55, v163
	v_mul_f32_e32 v164, v56, v164
	v_mul_f32_e32 v165, v57, v165
	v_mul_f32_e32 v162, v62, v162
	v_mul_f32_e32 v163, v63, v163
	v_mul_f32_e32 v164, v64, v164
	v_mul_f32_e32 v165, v65, v165
	v_cvt_pk_bf16_f32 v170, v162, v163
	v_cvt_pk_bf16_f32 v171, v164, v165
	s_nop 1
	v_permlane16_swap_b32_e32 v168, v170
	v_permlane16_swap_b32_e32 v169, v171
	global_store_dwordx4 v176, v[168:171], s[4:5] offset:0 sc1
	v_mul_f32_e32 v162, 0xbfb8aa3b, v114
	v_mul_f32_e32 v163, 0xbfb8aa3b, v115
	v_mul_f32_e32 v164, 0xbfb8aa3b, v116
	v_mul_f32_e32 v165, 0xbfb8aa3b, v117
	v_exp_f32_e32 v162, v162
	v_exp_f32_e32 v163, v163
	v_exp_f32_e32 v164, v164
	v_exp_f32_e32 v165, v165
	v_add_f32_e32 v162, 1.0, v162
	v_add_f32_e32 v163, 1.0, v163
	v_add_f32_e32 v164, 1.0, v164
	v_add_f32_e32 v165, 1.0, v165
	v_rcp_f32_e32 v162, v162
	v_rcp_f32_e32 v163, v163
	v_rcp_f32_e32 v164, v164
	v_rcp_f32_e32 v165, v165
	v_mul_f32_e32 v162, v114, v162
	v_mul_f32_e32 v163, v115, v163
	v_mul_f32_e32 v164, v116, v164
	v_mul_f32_e32 v165, v117, v165
	v_mul_f32_e32 v162, v122, v162
	v_mul_f32_e32 v163, v123, v163
	v_mul_f32_e32 v164, v124, v164
	v_mul_f32_e32 v165, v125, v165
	v_cvt_pk_bf16_f32 v172, v162, v163
	v_cvt_pk_bf16_f32 v173, v164, v165
	v_mul_f32_e32 v162, 0xbfb8aa3b, v118
	v_mul_f32_e32 v163, 0xbfb8aa3b, v119
	v_mul_f32_e32 v164, 0xbfb8aa3b, v120
	v_mul_f32_e32 v165, 0xbfb8aa3b, v121
	v_exp_f32_e32 v162, v162
	v_exp_f32_e32 v163, v163
	v_exp_f32_e32 v164, v164
	v_exp_f32_e32 v165, v165
	v_add_f32_e32 v162, 1.0, v162
	v_add_f32_e32 v163, 1.0, v163
	v_add_f32_e32 v164, 1.0, v164
	v_add_f32_e32 v165, 1.0, v165
	v_rcp_f32_e32 v162, v162
	v_rcp_f32_e32 v163, v163
	v_rcp_f32_e32 v164, v164
	v_rcp_f32_e32 v165, v165
	v_mul_f32_e32 v162, v118, v162
	v_mul_f32_e32 v163, v119, v163
	v_mul_f32_e32 v164, v120, v164
	v_mul_f32_e32 v165, v121, v165
	v_mul_f32_e32 v162, v126, v162
	v_mul_f32_e32 v163, v127, v163
	v_mul_f32_e32 v164, v128, v164
	v_mul_f32_e32 v165, v129, v165
	v_cvt_pk_bf16_f32 v174, v162, v163
	v_cvt_pk_bf16_f32 v175, v164, v165
	s_nop 1
	v_permlane16_swap_b32_e32 v172, v174
	v_permlane16_swap_b32_e32 v173, v175
	global_store_dwordx4 v176, v[172:175], s[4:5] offset:128 sc1
	s_add_u32 s10, s10, 32
	s_cmp_lt_u32 s10, 64
	s_cbranch_scc1 .Lg2_a_item1
	s_cmp_lt_u32 s15, 8
	s_cbranch_scc0 .Lg2_a_noleft5
	s_lshr_b32 s12, s15, 2
	s_add_u32 s12, s12, 4
	s_mov_b32 s11, 10
	s_and_b32 s16, s15, 3
	s_lshl_b32 s16, s16, 6
	s_and_b32 s17, s14, 3
	s_mul_i32 s17, s17, 6
	s_add_u32 s12, s12, s17
	s_lshl_b32 s12, s12, 8
	s_add_u32 s12, s12, s16
	s_lshr_b32 s17, s14, 2
	s_mul_i32 s17, s17, 22
	s_lshl_b32 s11, s11, 1
	s_add_u32 s11, s11, s17
	s_lshl_b32 s16, s12, 11
	s_add_u32 s0, s24, s16
	s_addc_u32 s1, s25, 0
	s_lshl_b32 s16, s11, 18
	s_add_u32 s2, s40, s16
	s_addc_u32 s3, s41, 0
	s_mul_i32 s16, s12, 0x1600
	s_lshl_b32 s17, s11, 7
	s_add_u32 s16, s16, s17
	s_add_u32 s4, s26, s16
	s_addc_u32 s5, s27, 0
	v_lshrrev_b32_e32 v141, 8, v142
	v_lshlrev_b32_e32 v141, 17, v141
	v_sub_u32_e32 v141, v136, v141
	s_and_b32 s17, s6, 0xfff
	s_add_u32 m0, s17, 0x0
	s_nop 0
	global_load_lds_dwordx4 v141, s[0:1]
	s_add_u32 m0, s6, 0x4000
	s_nop 0
	global_load_lds_dwordx4 v136, s[2:3]
	s_add_u32 m0, s6, 0x6000
	s_nop 0
	global_load_lds_dwordx4 v137, s[2:3]
	s_add_u32 s0, s0, 64
	s_addc_u32 s1, s1, 0
	s_add_u32 s2, s2, 64
	s_addc_u32 s3, s3, 0
	s_add_u32 m0, s17, 0x8000
	s_nop 0
	global_load_lds_dwordx4 v141, s[0:1]
	s_add_u32 m0, s6, 0xc000
	s_nop 0
	global_load_lds_dwordx4 v136, s[2:3]
	s_add_u32 m0, s6, 0xe000
	s_nop 0
	global_load_lds_dwordx4 v137, s[2:3]
	s_add_u32 s0, s0, 64
	s_addc_u32 s1, s1, 0
	s_add_u32 s2, s2, 64
	s_addc_u32 s3, s3, 0
	s_add_u32 m0, s17, 0x10000
	s_nop 0
	global_load_lds_dwordx4 v141, s[0:1]
	s_add_u32 m0, s6, 0x14000
	s_nop 0
	global_load_lds_dwordx4 v136, s[2:3]
	s_add_u32 m0, s6, 0x16000
	s_nop 0
	global_load_lds_dwordx4 v137, s[2:3]
	s_add_u32 s0, s0, 64
	s_addc_u32 s1, s1, 0
	s_add_u32 s2, s2, 64
	s_addc_u32 s3, s3, 0
	v_lshrrev_b32_e32 v140, 7, v142
	v_lshlrev_b32_e32 v139, 12, v140
	v_sub_u32_e32 v134, v134, v139
	v_lshl_add_u32 v134, v140, 10, v134
	v_mul_u32_u24_e32 v139, 0x42000, v140
	v_sub_u32_e32 v138, v138, v139
	v_mov_b32_e32 v2, 0
	v_mov_b32_e32 v3, 0
	v_mov_b32_e32 v4, 0
	v_mov_b32_e32 v5, 0
	v_mov_b32_e32 v6, 0
	v_mov_b32_e32 v7, 0
	v_mov_b32_e32 v8, 0
	v_mov_b32_e32 v9, 0
	v_mov_b32_e32 v10, 0
	v_mov_b32_e32 v11, 0
	v_mov_b32_e32 v12, 0
	v_mov_b32_e32 v13, 0
	v_mov_b32_e32 v14, 0
	v_mov_b32_e32 v15, 0
	v_mov_b32_e32 v16, 0
	v_mov_b32_e32 v17, 0
	v_mov_b32_e32 v66, 0
	v_mov_b32_e32 v67, 0
	v_mov_b32_e32 v68, 0
	v_mov_b32_e32 v69, 0
	v_mov_b32_e32 v70, 0
	v_mov_b32_e32 v71, 0
	v_mov_b32_e32 v72, 0
	v_mov_b32_e32 v73, 0
	v_mov_b32_e32 v74, 0
	v_mov_b32_e32 v75, 0
	v_mov_b32_e32 v76, 0
	v_mov_b32_e32 v77, 0
	v_mov_b32_e32 v78, 0
	v_mov_b32_e32 v79, 0
	v_mov_b32_e32 v80, 0
	v_mov_b32_e32 v81, 0

.LBB0_277:
.Lgb_gwin:
	s_waitcnt vmcnt(6)
	s_barrier
	s_mul_i32 s7, s6, 0xc000
	v_add_u32_e32 v81, s7, v80
	v_add_u32_e32 v161, s7, v79
	ds_read_b128 v[82:85], v81 offset:0
	ds_read_b128 v[86:89], v81 offset:2048
	ds_read_b128 v[90:93], v81 offset:4096
	ds_read_b128 v[94:97], v81 offset:6144
	ds_read_b128 v[98:101], v161 offset:0
	ds_read_b128 v[102:105], v161 offset:2048
	ds_read_b128 v[106:109], v161 offset:4096
	ds_read_b128 v[110:113], v161 offset:6144
	s_mul_i32 s7, s3, 0xc000
	v_add_u32_e32 v218, s7, v78
	s_nop 0
	v_readfirstlane_b32 s7, v218
	s_add_u32 m0, s7, 0x0
	v_lshl_add_u64 v[218:219], v[76:77], 0, s[4:5]
	global_load_lds_dwordx4 v[218:219], off
	s_add_u32 m0, s7, 0x2000
	v_lshl_add_u64 v[218:219], v[74:75], 0, s[4:5]
	global_load_lds_dwordx4 v[218:219], off
	s_add_u32 m0, s7, 0x4000
	v_lshl_add_u64 v[218:219], v[72:73], 0, s[4:5]
	global_load_lds_dwordx4 v[218:219], off
	s_add_u32 m0, s7, 0x6000
	v_lshl_add_u64 v[218:219], v[70:71], 0, s[4:5]
	global_load_lds_dwordx4 v[218:219], off
	s_add_u32 m0, s7, 0x8000
	v_lshl_add_u64 v[218:219], v[68:69], 0, s[4:5]
	global_load_lds_dwordx4 v[218:219], off
	s_add_u32 m0, s7, 0xa000
	v_lshl_add_u64 v[218:219], v[66:67], 0, s[4:5]
	global_load_lds_dwordx4 v[218:219], off
	ds_read_b128 v[114:117], v81 offset:1024
	ds_read_b128 v[118:121], v81 offset:3072
	ds_read_b128 v[122:125], v81 offset:5120
	ds_read_b128 v[126:129], v81 offset:7168
	ds_read_b128 v[134:137], v161 offset:1024
	ds_read_b128 v[138:141], v161 offset:3072
	ds_read_b128 v[162:165], v161 offset:5120
	ds_read_b128 v[166:169], v161 offset:7168
	s_waitcnt lgkmcnt(8)
	v_mfma_f32_16x16x32_bf16 v[62:65], v[98:101], v[82:85], v[62:65]
	v_mfma_f32_16x16x32_bf16 v[58:61], v[102:105], v[82:85], v[58:61]
	v_mfma_f32_16x16x32_bf16 v[54:57], v[106:109], v[82:85], v[54:57]
	v_mfma_f32_16x16x32_bf16 v[50:53], v[110:113], v[82:85], v[50:53]
	v_mfma_f32_16x16x32_bf16 v[46:49], v[98:101], v[86:89], v[46:49]
	v_mfma_f32_16x16x32_bf16 v[42:45], v[102:105], v[86:89], v[42:45]
	v_mfma_f32_16x16x32_bf16 v[38:41], v[106:109], v[86:89], v[38:41]
	v_mfma_f32_16x16x32_bf16 v[34:37], v[110:113], v[86:89], v[34:37]
	v_mfma_f32_16x16x32_bf16 v[30:33], v[98:101], v[90:93], v[30:33]
	v_mfma_f32_16x16x32_bf16 v[26:29], v[102:105], v[90:93], v[26:29]
	v_mfma_f32_16x16x32_bf16 v[22:25], v[106:109], v[90:93], v[22:25]
	v_mfma_f32_16x16x32_bf16 v[18:21], v[110:113], v[90:93], v[18:21]
	v_mfma_f32_16x16x32_bf16 v[14:17], v[98:101], v[94:97], v[14:17]
	v_mfma_f32_16x16x32_bf16 v[10:13], v[102:105], v[94:97], v[10:13]
	v_mfma_f32_16x16x32_bf16 v[6:9], v[106:109], v[94:97], v[6:9]
	v_mfma_f32_16x16x32_bf16 v[2:5], v[110:113], v[94:97], v[2:5]
	s_waitcnt lgkmcnt(0)
	s_add_i32 s7, s6, 1
	s_cmp_lg_u32 s6, 2
	s_cselect_b32 s6, s7, 0
	s_add_i32 s7, s3, 1
	s_cmp_lg_u32 s3, 2
	s_cselect_b32 s3, s7, 0
	s_add_u32 s4, s4, 0x80
	s_addc_u32 s5, s5, 0
.Lgbl_gwin:
	s_waitcnt vmcnt(6)
	s_barrier
	s_mul_i32 s7, s6, 0xc000
	v_add_u32_e32 v81, s7, v80
	v_add_u32_e32 v161, s7, v79
	ds_read_b128 v[82:85], v81 offset:0
	ds_read_b128 v[86:89], v81 offset:2048
	ds_read_b128 v[90:93], v81 offset:4096
	ds_read_b128 v[94:97], v81 offset:6144
	ds_read_b128 v[98:101], v161 offset:0
	ds_read_b128 v[102:105], v161 offset:2048
	ds_read_b128 v[106:109], v161 offset:4096
	ds_read_b128 v[110:113], v161 offset:6144
	s_mul_i32 s7, s3, 0xc000
	v_add_u32_e32 v218, s7, v78
	s_nop 0
	v_readfirstlane_b32 s7, v218
	v_mfma_f32_16x16x32_bf16 v[62:65], v[134:137], v[114:117], v[62:65]
	v_mfma_f32_16x16x32_bf16 v[58:61], v[138:141], v[114:117], v[58:61]
	s_add_u32 m0, s7, 0x0
	v_lshl_add_u64 v[218:219], v[76:77], 0, s[4:5]
	global_load_lds_dwordx4 v[218:219], off
	v_mfma_f32_16x16x32_bf16 v[54:57], v[162:165], v[114:117], v[54:57]
	v_mfma_f32_16x16x32_bf16 v[50:53], v[166:169], v[114:117], v[50:53]
	s_add_u32 m0, s7, 0x2000
	v_lshl_add_u64 v[218:219], v[74:75], 0, s[4:5]
	global_load_lds_dwordx4 v[218:219], off
	v_mfma_f32_16x16x32_bf16 v[46:49], v[134:137], v[118:121], v[46:49]
	v_mfma_f32_16x16x32_bf16 v[42:45], v[138:141], v[118:121], v[42:45]
	s_add_u32 m0, s7, 0x4000
	v_lshl_add_u64 v[218:219], v[72:73], 0, s[4:5]
	global_load_lds_dwordx4 v[218:219], off
	v_mfma_f32_16x16x32_bf16 v[38:41], v[162:165], v[118:121], v[38:41]
	v_mfma_f32_16x16x32_bf16 v[34:37], v[166:169], v[118:121], v[34:37]
	s_add_u32 m0, s7, 0x6000
	v_lshl_add_u64 v[218:219], v[70:71], 0, s[4:5]
	global_load_lds_dwordx4 v[218:219], off
	v_mfma_f32_16x16x32_bf16 v[30:33], v[134:137], v[122:125], v[30:33]
	v_mfma_f32_16x16x32_bf16 v[26:29], v[138:141], v[122:125], v[26:29]
	s_add_u32 m0, s7, 0x8000
	v_lshl_add_u64 v[218:219], v[68:69], 0, s[4:5]
	global_load_lds_dwordx4 v[218:219], off
	v_mfma_f32_16x16x32_bf16 v[22:25], v[162:165], v[122:125], v[22:25]
	v_mfma_f32_16x16x32_bf16 v[18:21], v[166:169], v[122:125], v[18:21]
	s_add_u32 m0, s7, 0xa000
	v_lshl_add_u64 v[218:219], v[66:67], 0, s[4:5]
	global_load_lds_dwordx4 v[218:219], off
	v_mfma_f32_16x16x32_bf16 v[14:17], v[134:137], v[126:129], v[14:17]
	v_mfma_f32_16x16x32_bf16 v[10:13], v[138:141], v[126:129], v[10:13]
	v_mfma_f32_16x16x32_bf16 v[6:9], v[162:165], v[126:129], v[6:9]
	v_mfma_f32_16x16x32_bf16 v[2:5], v[166:169], v[126:129], v[2:5]
	ds_read_b128 v[114:117], v81 offset:1024
	ds_read_b128 v[118:121], v81 offset:3072
	ds_read_b128 v[122:125], v81 offset:5120
	ds_read_b128 v[126:129], v81 offset:7168
	ds_read_b128 v[134:137], v161 offset:1024
	ds_read_b128 v[138:141], v161 offset:3072
	ds_read_b128 v[162:165], v161 offset:5120
	ds_read_b128 v[166:169], v161 offset:7168
	s_waitcnt lgkmcnt(8)
	v_mfma_f32_16x16x32_bf16 v[62:65], v[98:101], v[82:85], v[62:65]
	v_mfma_f32_16x16x32_bf16 v[58:61], v[102:105], v[82:85], v[58:61]
	v_mfma_f32_16x16x32_bf16 v[54:57], v[106:109], v[82:85], v[54:57]
	v_mfma_f32_16x16x32_bf16 v[50:53], v[110:113], v[82:85], v[50:53]
	v_mfma_f32_16x16x32_bf16 v[46:49], v[98:101], v[86:89], v[46:49]
	v_mfma_f32_16x16x32_bf16 v[42:45], v[102:105], v[86:89], v[42:45]
	v_mfma_f32_16x16x32_bf16 v[38:41], v[106:109], v[86:89], v[38:41]
	v_mfma_f32_16x16x32_bf16 v[34:37], v[110:113], v[86:89], v[34:37]
	v_mfma_f32_16x16x32_bf16 v[30:33], v[98:101], v[90:93], v[30:33]
	v_mfma_f32_16x16x32_bf16 v[26:29], v[102:105], v[90:93], v[26:29]
	v_mfma_f32_16x16x32_bf16 v[22:25], v[106:109], v[90:93], v[22:25]
	v_mfma_f32_16x16x32_bf16 v[18:21], v[110:113], v[90:93], v[18:21]
	v_mfma_f32_16x16x32_bf16 v[14:17], v[98:101], v[94:97], v[14:17]
	v_mfma_f32_16x16x32_bf16 v[10:13], v[102:105], v[94:97], v[10:13]
	v_mfma_f32_16x16x32_bf16 v[6:9], v[106:109], v[94:97], v[6:9]
	v_mfma_f32_16x16x32_bf16 v[2:5], v[110:113], v[94:97], v[2:5]
	s_waitcnt lgkmcnt(0)
	s_add_i32 s7, s6, 1
	s_cmp_lg_u32 s6, 2
	s_cselect_b32 s6, s7, 0
	s_add_i32 s7, s3, 1
	s_cmp_lg_u32 s3, 2
	s_cselect_b32 s3, s7, 0
	s_add_u32 s4, s4, 0x80
	s_addc_u32 s5, s5, 0
	s_cmpk_lg_i32 s4, 0x700
	s_cbranch_scc1 .Lgbl_gwin
	s_waitcnt vmcnt(6)
	s_barrier
	s_mul_i32 s7, s6, 0xc000
	v_add_u32_e32 v81, s7, v80
	v_add_u32_e32 v161, s7, v79
	ds_read_b128 v[82:85], v81 offset:0
	ds_read_b128 v[86:89], v81 offset:2048
	ds_read_b128 v[90:93], v81 offset:4096
	ds_read_b128 v[94:97], v81 offset:6144
	ds_read_b128 v[98:101], v161 offset:0
	ds_read_b128 v[102:105], v161 offset:2048
	ds_read_b128 v[106:109], v161 offset:4096
	ds_read_b128 v[110:113], v161 offset:6144
	v_mfma_f32_16x16x32_bf16 v[62:65], v[134:137], v[114:117], v[62:65]
	v_mfma_f32_16x16x32_bf16 v[58:61], v[138:141], v[114:117], v[58:61]
	v_mfma_f32_16x16x32_bf16 v[54:57], v[162:165], v[114:117], v[54:57]
	v_mfma_f32_16x16x32_bf16 v[50:53], v[166:169], v[114:117], v[50:53]
	v_mfma_f32_16x16x32_bf16 v[46:49], v[134:137], v[118:121], v[46:49]
	v_mfma_f32_16x16x32_bf16 v[42:45], v[138:141], v[118:121], v[42:45]
	v_mfma_f32_16x16x32_bf16 v[38:41], v[162:165], v[118:121], v[38:41]
	v_mfma_f32_16x16x32_bf16 v[34:37], v[166:169], v[118:121], v[34:37]
	v_mfma_f32_16x16x32_bf16 v[30:33], v[134:137], v[122:125], v[30:33]
	v_mfma_f32_16x16x32_bf16 v[26:29], v[138:141], v[122:125], v[26:29]
	v_mfma_f32_16x16x32_bf16 v[22:25], v[162:165], v[122:125], v[22:25]
	v_mfma_f32_16x16x32_bf16 v[18:21], v[166:169], v[122:125], v[18:21]
	v_mfma_f32_16x16x32_bf16 v[14:17], v[134:137], v[126:129], v[14:17]
	v_mfma_f32_16x16x32_bf16 v[10:13], v[138:141], v[126:129], v[10:13]
	v_mfma_f32_16x16x32_bf16 v[6:9], v[162:165], v[126:129], v[6:9]
	v_mfma_f32_16x16x32_bf16 v[2:5], v[166:169], v[126:129], v[2:5]
	ds_read_b128 v[114:117], v81 offset:1024
	ds_read_b128 v[118:121], v81 offset:3072
	ds_read_b128 v[122:125], v81 offset:5120
	ds_read_b128 v[126:129], v81 offset:7168
	ds_read_b128 v[134:137], v161 offset:1024
	ds_read_b128 v[138:141], v161 offset:3072
	ds_read_b128 v[162:165], v161 offset:5120
	ds_read_b128 v[166:169], v161 offset:7168
	s_waitcnt lgkmcnt(8)
	v_mfma_f32_16x16x32_bf16 v[62:65], v[98:101], v[82:85], v[62:65]
	v_mfma_f32_16x16x32_bf16 v[58:61], v[102:105], v[82:85], v[58:61]
	v_mfma_f32_16x16x32_bf16 v[54:57], v[106:109], v[82:85], v[54:57]
	v_mfma_f32_16x16x32_bf16 v[50:53], v[110:113], v[82:85], v[50:53]
	v_mfma_f32_16x16x32_bf16 v[46:49], v[98:101], v[86:89], v[46:49]
	v_mfma_f32_16x16x32_bf16 v[42:45], v[102:105], v[86:89], v[42:45]
	v_mfma_f32_16x16x32_bf16 v[38:41], v[106:109], v[86:89], v[38:41]
	v_mfma_f32_16x16x32_bf16 v[34:37], v[110:113], v[86:89], v[34:37]
	v_mfma_f32_16x16x32_bf16 v[30:33], v[98:101], v[90:93], v[30:33]
	v_mfma_f32_16x16x32_bf16 v[26:29], v[102:105], v[90:93], v[26:29]
	v_mfma_f32_16x16x32_bf16 v[22:25], v[106:109], v[90:93], v[22:25]
	v_mfma_f32_16x16x32_bf16 v[18:21], v[110:113], v[90:93], v[18:21]
	v_mfma_f32_16x16x32_bf16 v[14:17], v[98:101], v[94:97], v[14:17]
	v_mfma_f32_16x16x32_bf16 v[10:13], v[102:105], v[94:97], v[10:13]
	v_mfma_f32_16x16x32_bf16 v[6:9], v[106:109], v[94:97], v[6:9]
	v_mfma_f32_16x16x32_bf16 v[2:5], v[110:113], v[94:97], v[2:5]
	s_waitcnt lgkmcnt(0)
	s_add_i32 s7, s6, 1
	s_cmp_lg_u32 s6, 2
	s_cselect_b32 s6, s7, 0
	s_add_i32 s7, s3, 1
	s_cmp_lg_u32 s3, 2
	s_cselect_b32 s3, s7, 0
	s_waitcnt vmcnt(0)
	s_barrier
	s_mul_i32 s7, s6, 0xc000
	v_add_u32_e32 v81, s7, v80
	v_add_u32_e32 v161, s7, v79
	ds_read_b128 v[82:85], v81 offset:0
	ds_read_b128 v[86:89], v81 offset:2048
	ds_read_b128 v[90:93], v81 offset:4096
	ds_read_b128 v[94:97], v81 offset:6144
	ds_read_b128 v[98:101], v161 offset:0
	ds_read_b128 v[102:105], v161 offset:2048
	ds_read_b128 v[106:109], v161 offset:4096
	ds_read_b128 v[110:113], v161 offset:6144
	v_mfma_f32_16x16x32_bf16 v[62:65], v[134:137], v[114:117], v[62:65]
	v_mfma_f32_16x16x32_bf16 v[58:61], v[138:141], v[114:117], v[58:61]
	v_mfma_f32_16x16x32_bf16 v[54:57], v[162:165], v[114:117], v[54:57]
	v_mfma_f32_16x16x32_bf16 v[50:53], v[166:169], v[114:117], v[50:53]
	v_mfma_f32_16x16x32_bf16 v[46:49], v[134:137], v[118:121], v[46:49]
	v_mfma_f32_16x16x32_bf16 v[42:45], v[138:141], v[118:121], v[42:45]
	v_mfma_f32_16x16x32_bf16 v[38:41], v[162:165], v[118:121], v[38:41]
	v_mfma_f32_16x16x32_bf16 v[34:37], v[166:169], v[118:121], v[34:37]
	v_mfma_f32_16x16x32_bf16 v[30:33], v[134:137], v[122:125], v[30:33]
	v_mfma_f32_16x16x32_bf16 v[26:29], v[138:141], v[122:125], v[26:29]
	v_mfma_f32_16x16x32_bf16 v[22:25], v[162:165], v[122:125], v[22:25]
	v_mfma_f32_16x16x32_bf16 v[18:21], v[166:169], v[122:125], v[18:21]
	v_mfma_f32_16x16x32_bf16 v[14:17], v[134:137], v[126:129], v[14:17]
	v_mfma_f32_16x16x32_bf16 v[10:13], v[138:141], v[126:129], v[10:13]
	v_mfma_f32_16x16x32_bf16 v[6:9], v[162:165], v[126:129], v[6:9]
	v_mfma_f32_16x16x32_bf16 v[2:5], v[166:169], v[126:129], v[2:5]
	ds_read_b128 v[114:117], v81 offset:1024
	ds_read_b128 v[118:121], v81 offset:3072
	ds_read_b128 v[122:125], v81 offset:5120
	ds_read_b128 v[126:129], v81 offset:7168
	ds_read_b128 v[134:137], v161 offset:1024
	ds_read_b128 v[138:141], v161 offset:3072
	ds_read_b128 v[162:165], v161 offset:5120
	ds_read_b128 v[166:169], v161 offset:7168
	s_waitcnt lgkmcnt(8)
	v_mfma_f32_16x16x32_bf16 v[62:65], v[98:101], v[82:85], v[62:65]
	v_mfma_f32_16x16x32_bf16 v[58:61], v[102:105], v[82:85], v[58:61]
	v_mfma_f32_16x16x32_bf16 v[54:57], v[106:109], v[82:85], v[54:57]
	v_mfma_f32_16x16x32_bf16 v[50:53], v[110:113], v[82:85], v[50:53]
	v_mfma_f32_16x16x32_bf16 v[46:49], v[98:101], v[86:89], v[46:49]
	v_mfma_f32_16x16x32_bf16 v[42:45], v[102:105], v[86:89], v[42:45]
	v_mfma_f32_16x16x32_bf16 v[38:41], v[106:109], v[86:89], v[38:41]
	v_mfma_f32_16x16x32_bf16 v[34:37], v[110:113], v[86:89], v[34:37]
	v_mfma_f32_16x16x32_bf16 v[30:33], v[98:101], v[90:93], v[30:33]
	v_mfma_f32_16x16x32_bf16 v[26:29], v[102:105], v[90:93], v[26:29]
	v_mfma_f32_16x16x32_bf16 v[22:25], v[106:109], v[90:93], v[22:25]
	v_mfma_f32_16x16x32_bf16 v[18:21], v[110:113], v[90:93], v[18:21]
	v_mfma_f32_16x16x32_bf16 v[14:17], v[98:101], v[94:97], v[14:17]
	v_mfma_f32_16x16x32_bf16 v[10:13], v[102:105], v[94:97], v[10:13]
	v_mfma_f32_16x16x32_bf16 v[6:9], v[106:109], v[94:97], v[6:9]
	v_mfma_f32_16x16x32_bf16 v[2:5], v[110:113], v[94:97], v[2:5]
	s_waitcnt lgkmcnt(0)
	s_add_i32 s7, s6, 1
	s_cmp_lg_u32 s6, 2
	s_cselect_b32 s6, s7, 0
	s_add_i32 s7, s3, 1
	s_cmp_lg_u32 s3, 2
	s_cselect_b32 s3, s7, 0
	v_mfma_f32_16x16x32_bf16 v[62:65], v[134:137], v[114:117], v[62:65]
	v_mfma_f32_16x16x32_bf16 v[58:61], v[138:141], v[114:117], v[58:61]
	v_mfma_f32_16x16x32_bf16 v[54:57], v[162:165], v[114:117], v[54:57]
	v_mfma_f32_16x16x32_bf16 v[50:53], v[166:169], v[114:117], v[50:53]
	v_mfma_f32_16x16x32_bf16 v[46:49], v[134:137], v[118:121], v[46:49]
	v_mfma_f32_16x16x32_bf16 v[42:45], v[138:141], v[118:121], v[42:45]
	v_mfma_f32_16x16x32_bf16 v[38:41], v[162:165], v[118:121], v[38:41]
	v_mfma_f32_16x16x32_bf16 v[34:37], v[166:169], v[118:121], v[34:37]
	v_mfma_f32_16x16x32_bf16 v[30:33], v[134:137], v[122:125], v[30:33]
	v_mfma_f32_16x16x32_bf16 v[26:29], v[138:141], v[122:125], v[26:29]
	v_mfma_f32_16x16x32_bf16 v[22:25], v[162:165], v[122:125], v[22:25]
	v_mfma_f32_16x16x32_bf16 v[18:21], v[166:169], v[122:125], v[18:21]
	v_mfma_f32_16x16x32_bf16 v[14:17], v[134:137], v[126:129], v[14:17]
	v_mfma_f32_16x16x32_bf16 v[10:13], v[138:141], v[126:129], v[10:13]
	v_mfma_f32_16x16x32_bf16 v[6:9], v[162:165], v[126:129], v[6:9]
	v_mfma_f32_16x16x32_bf16 v[2:5], v[166:169], v[126:129], v[2:5]
.Lgd_gwin:
	s_nop 7
	s_nop 1
	v_bfe_u32 v161, v0, 6, 1
	v_and_b32_e32 v134, 15, v0
	v_bfe_u32 v162, v0, 4, 2
	v_ashrrev_i32_e32 v0, 1, v0
	v_and_b32_e32 v163, 0xffffffc0, v0
	s_cmp_gt_i32 s18, 7
	s_mov_b64 s[4:5], -1
	s_cbranch_scc0 .LBB0_316
	s_cmp_gt_u32 s18, 15
	s_cbranch_scc0 .LBB0_305
	s_cmpk_gt_i32 s16, 0x6f
	s_cselect_b64 s[4:5], -1, 0
	s_add_i32 s3, s2, 0xfffff000
	s_lshr_b32 s3, s3, 10
	s_cmpk_lt_i32 s16, 0x70
	s_cselect_b64 s[6:7], -1, 0
	s_and_b64 s[8:9], s[6:7], exec
	s_movk_i32 s8, 0x70
	s_cselect_b32 s8, s8, 0x300
	s_and_b32 s8, s8, s2
	v_add_u32_e32 v136, s8, v163
	s_cmp_gt_u32 s18, 31
	s_mov_b64 s[8:9], -1
	s_cbranch_scc0 .LBB0_290
	s_cmp_gt_u32 s18, 39
	s_cbranch_scc0 .LBB0_283
	v_or_b32_e32 v0, s2, v134
	v_add_u32_e32 v66, v0, v163
	v_ashrrev_i32_e32 v67, 31, v66
	v_lshlrev_b64 v[68:69], 12, v[66:67]
	v_mul_f32_e32 v67, 0xbfb8aa3b, v62
	v_mul_f32_e32 v74, 0xbfb8aa3b, v63
	v_mul_f32_e32 v75, 0xbfb8aa3b, v64
	v_mul_f32_e32 v76, 0xbfb8aa3b, v65
	v_exp_f32_e32 v67, v67
	v_exp_f32_e32 v74, v74
	v_exp_f32_e32 v75, v75
	v_exp_f32_e32 v76, v76
	s_lshl_b64 s[8:9], s[40:41], 1
	s_add_u32 s8, s48, s8
	s_addc_u32 s9, s49, s9
	v_add_f32_e32 v67, 1.0, v67
	v_add_f32_e32 v74, 1.0, v74
	v_add_f32_e32 v75, 1.0, v75
	v_add_f32_e32 v76, 1.0, v76
	v_lshl_add_u64 v[68:69], s[8:9], 0, v[68:69]
	v_lshlrev_b32_e32 v0, 7, v161
	v_rcp_f32_e32 v67, v67
	v_rcp_f32_e32 v74, v74
	v_rcp_f32_e32 v75, v75
	v_rcp_f32_e32 v76, v76
	v_lshl_add_u64 v[70:71], v[68:69], 0, v[0:1]
	v_lshlrev_b32_e32 v68, 3, v162
	v_mov_b32_e32 v69, v1
	v_lshl_add_u64 v[72:73], v[70:71], 0, v[68:69]
	s_mov_b64 s[38:39], 0xa15d800
	s_mov_b32 s10, 0xa15d000
	v_lshl_add_u64 v[70:71], v[72:73], 0, s[38:39]
	v_add_co_u32_e32 v72, vcc, s10, v72
	v_cvt_pk_bf16_f32 v74, v67, v74
	v_cvt_pk_bf16_f32 v75, v75, v76
	v_addc_co_u32_e32 v73, vcc, 0, v73, vcc
	global_store_dwordx2 v[72:73], v[74:75], off offset:2048
	v_mul_f32_e32 v67, 0xbfb8aa3b, v58
	v_mul_f32_e32 v72, 0xbfb8aa3b, v59
	v_mul_f32_e32 v73, 0xbfb8aa3b, v60
	v_mul_f32_e32 v74, 0xbfb8aa3b, v61
	v_exp_f32_e32 v67, v67
	v_exp_f32_e32 v72, v72
	v_exp_f32_e32 v73, v73
	v_exp_f32_e32 v74, v74
	v_add_f32_e32 v67, 1.0, v67
	v_add_f32_e32 v72, 1.0, v72
	v_add_f32_e32 v73, 1.0, v73
	v_add_f32_e32 v74, 1.0, v74
	v_rcp_f32_e32 v67, v67
	v_rcp_f32_e32 v72, v72
	v_rcp_f32_e32 v73, v73
	v_rcp_f32_e32 v74, v74
	v_mul_f32_e32 v75, 0xbfb8aa3b, v48
	v_cvt_pk_bf16_f32 v72, v67, v72
	v_mul_f32_e32 v67, 0xbfb8aa3b, v54
	v_cvt_pk_bf16_f32 v73, v73, v74
	global_store_dwordx2 v[70:71], v[72:73], off offset:32
	v_mul_f32_e32 v72, 0xbfb8aa3b, v55
	v_mul_f32_e32 v73, 0xbfb8aa3b, v56
	v_mul_f32_e32 v74, 0xbfb8aa3b, v57
	v_exp_f32_e32 v67, v67
	v_exp_f32_e32 v72, v72
	v_exp_f32_e32 v73, v73
	v_exp_f32_e32 v74, v74
	v_add_f32_e32 v67, 1.0, v67
	v_add_f32_e32 v72, 1.0, v72
	v_add_f32_e32 v73, 1.0, v73
	v_add_f32_e32 v74, 1.0, v74
	v_rcp_f32_e32 v67, v67
	v_rcp_f32_e32 v72, v72
	v_rcp_f32_e32 v73, v73
	v_rcp_f32_e32 v74, v74
	v_mul_f32_e32 v76, 0xbfb8aa3b, v49
	v_cvt_pk_bf16_f32 v72, v67, v72
	v_mul_f32_e32 v67, 0xbfb8aa3b, v50
	v_cvt_pk_bf16_f32 v73, v73, v74
	global_store_dwordx2 v[70:71], v[72:73], off offset:64
	v_mul_f32_e32 v72, 0xbfb8aa3b, v51
	v_mul_f32_e32 v73, 0xbfb8aa3b, v52
	v_mul_f32_e32 v74, 0xbfb8aa3b, v53
	v_exp_f32_e32 v67, v67
	v_exp_f32_e32 v72, v72
	v_exp_f32_e32 v73, v73
	v_exp_f32_e32 v74, v74
	v_add_f32_e32 v67, 1.0, v67
	v_add_f32_e32 v72, 1.0, v72
	v_add_f32_e32 v73, 1.0, v73
	v_add_f32_e32 v74, 1.0, v74
	v_rcp_f32_e32 v67, v67
	v_rcp_f32_e32 v72, v72
	v_rcp_f32_e32 v73, v73
	v_rcp_f32_e32 v74, v74
	v_exp_f32_e32 v75, v75
	v_cvt_pk_bf16_f32 v72, v67, v72
	v_mul_f32_e32 v67, 0xbfb8aa3b, v46
	v_cvt_pk_bf16_f32 v73, v73, v74
	v_mul_f32_e32 v74, 0xbfb8aa3b, v47
	v_exp_f32_e32 v67, v67
	v_exp_f32_e32 v74, v74
	v_exp_f32_e32 v76, v76
	global_store_dwordx2 v[70:71], v[72:73], off offset:96
	v_or_b32_e32 v70, 16, v66
	v_ashrrev_i32_e32 v71, 31, v70
	v_lshlrev_b64 v[70:71], 12, v[70:71]
	v_add_f32_e32 v67, 1.0, v67
	v_add_f32_e32 v74, 1.0, v74
	v_add_f32_e32 v75, 1.0, v75
	v_add_f32_e32 v76, 1.0, v76
	v_lshl_add_u64 v[70:71], s[8:9], 0, v[70:71]
	v_rcp_f32_e32 v67, v67
	v_rcp_f32_e32 v74, v74
	v_rcp_f32_e32 v75, v75
	v_rcp_f32_e32 v76, v76
	v_lshl_add_u64 v[70:71], v[70:71], 0, v[0:1]
	v_lshl_add_u64 v[72:73], v[70:71], 0, v[68:69]
	v_lshl_add_u64 v[70:71], v[72:73], 0, s[38:39]
	v_add_co_u32_e32 v72, vcc, s10, v72
	v_cvt_pk_bf16_f32 v74, v67, v74
	v_cvt_pk_bf16_f32 v75, v75, v76
	v_addc_co_u32_e32 v73, vcc, 0, v73, vcc
	global_store_dwordx2 v[72:73], v[74:75], off offset:2048
	v_mul_f32_e32 v67, 0xbfb8aa3b, v42
	v_mul_f32_e32 v72, 0xbfb8aa3b, v43
	v_mul_f32_e32 v73, 0xbfb8aa3b, v44
	v_mul_f32_e32 v74, 0xbfb8aa3b, v45
	v_exp_f32_e32 v67, v67
	v_exp_f32_e32 v72, v72
	v_exp_f32_e32 v73, v73
	v_exp_f32_e32 v74, v74
	v_add_f32_e32 v67, 1.0, v67
	v_add_f32_e32 v72, 1.0, v72
	v_add_f32_e32 v73, 1.0, v73
	v_add_f32_e32 v74, 1.0, v74
	v_rcp_f32_e32 v67, v67
	v_rcp_f32_e32 v72, v72
	v_rcp_f32_e32 v73, v73
	v_rcp_f32_e32 v74, v74
	v_mul_f32_e32 v75, 0xbfb8aa3b, v32
	v_cvt_pk_bf16_f32 v72, v67, v72
	v_mul_f32_e32 v67, 0xbfb8aa3b, v38
	v_cvt_pk_bf16_f32 v73, v73, v74
	global_store_dwordx2 v[70:71], v[72:73], off offset:32
	v_mul_f32_e32 v72, 0xbfb8aa3b, v39
	v_mul_f32_e32 v73, 0xbfb8aa3b, v40
	v_mul_f32_e32 v74, 0xbfb8aa3b, v41
	v_exp_f32_e32 v67, v67
	v_exp_f32_e32 v72, v72
	v_exp_f32_e32 v73, v73
	v_exp_f32_e32 v74, v74
	v_add_f32_e32 v67, 1.0, v67
	v_add_f32_e32 v72, 1.0, v72
	v_add_f32_e32 v73, 1.0, v73
	v_add_f32_e32 v74, 1.0, v74
	v_rcp_f32_e32 v67, v67
	v_rcp_f32_e32 v72, v72
	v_rcp_f32_e32 v73, v73
	v_rcp_f32_e32 v74, v74
	v_mul_f32_e32 v76, 0xbfb8aa3b, v33
	v_cvt_pk_bf16_f32 v72, v67, v72
	v_mul_f32_e32 v67, 0xbfb8aa3b, v34
	v_cvt_pk_bf16_f32 v73, v73, v74
	global_store_dwordx2 v[70:71], v[72:73], off offset:64
	v_mul_f32_e32 v72, 0xbfb8aa3b, v35
	v_mul_f32_e32 v73, 0xbfb8aa3b, v36
	v_mul_f32_e32 v74, 0xbfb8aa3b, v37
	v_exp_f32_e32 v67, v67
	v_exp_f32_e32 v72, v72
	v_exp_f32_e32 v73, v73
	v_exp_f32_e32 v74, v74
	v_add_f32_e32 v67, 1.0, v67
	v_add_f32_e32 v72, 1.0, v72
	v_add_f32_e32 v73, 1.0, v73
	v_add_f32_e32 v74, 1.0, v74
	v_rcp_f32_e32 v67, v67
	v_rcp_f32_e32 v72, v72
	v_rcp_f32_e32 v73, v73
	v_rcp_f32_e32 v74, v74
	v_exp_f32_e32 v75, v75
	v_cvt_pk_bf16_f32 v72, v67, v72
	v_mul_f32_e32 v67, 0xbfb8aa3b, v30
	v_cvt_pk_bf16_f32 v73, v73, v74
	v_mul_f32_e32 v74, 0xbfb8aa3b, v31
	v_exp_f32_e32 v67, v67
	v_exp_f32_e32 v74, v74
	v_exp_f32_e32 v76, v76
	global_store_dwordx2 v[70:71], v[72:73], off offset:96
	v_or_b32_e32 v70, 32, v66
	v_ashrrev_i32_e32 v71, 31, v70
	v_lshlrev_b64 v[70:71], 12, v[70:71]
	v_add_f32_e32 v67, 1.0, v67
	v_add_f32_e32 v74, 1.0, v74
	v_add_f32_e32 v75, 1.0, v75
	v_add_f32_e32 v76, 1.0, v76
	v_lshl_add_u64 v[70:71], s[8:9], 0, v[70:71]
	v_rcp_f32_e32 v67, v67
	v_rcp_f32_e32 v74, v74
	v_rcp_f32_e32 v75, v75
	v_rcp_f32_e32 v76, v76
	v_lshl_add_u64 v[70:71], v[70:71], 0, v[0:1]
	v_lshl_add_u64 v[72:73], v[70:71], 0, v[68:69]
	v_lshl_add_u64 v[70:71], v[72:73], 0, s[38:39]
	v_add_co_u32_e32 v72, vcc, s10, v72
	v_cvt_pk_bf16_f32 v74, v67, v74
	v_cvt_pk_bf16_f32 v75, v75, v76
	v_addc_co_u32_e32 v73, vcc, 0, v73, vcc
	global_store_dwordx2 v[72:73], v[74:75], off offset:2048
	v_mul_f32_e32 v67, 0xbfb8aa3b, v26
	v_mul_f32_e32 v72, 0xbfb8aa3b, v27
	v_mul_f32_e32 v73, 0xbfb8aa3b, v28
	v_mul_f32_e32 v74, 0xbfb8aa3b, v29
	v_exp_f32_e32 v67, v67
	v_exp_f32_e32 v72, v72
	v_exp_f32_e32 v73, v73
	v_exp_f32_e32 v74, v74
	v_add_f32_e32 v67, 1.0, v67
	v_add_f32_e32 v72, 1.0, v72
	v_add_f32_e32 v73, 1.0, v73
	v_add_f32_e32 v74, 1.0, v74
	v_rcp_f32_e32 v67, v67
	v_rcp_f32_e32 v72, v72
	v_rcp_f32_e32 v73, v73
	v_rcp_f32_e32 v74, v74
	v_or_b32_e32 v66, 48, v66
	v_cvt_pk_bf16_f32 v72, v67, v72
	v_mul_f32_e32 v67, 0xbfb8aa3b, v22
	v_cvt_pk_bf16_f32 v73, v73, v74
	global_store_dwordx2 v[70:71], v[72:73], off offset:32
	v_mul_f32_e32 v72, 0xbfb8aa3b, v23
	v_mul_f32_e32 v73, 0xbfb8aa3b, v24
	v_mul_f32_e32 v74, 0xbfb8aa3b, v25
	v_exp_f32_e32 v67, v67
	v_exp_f32_e32 v72, v72
	v_exp_f32_e32 v73, v73
	v_exp_f32_e32 v74, v74
	v_add_f32_e32 v67, 1.0, v67
	v_add_f32_e32 v72, 1.0, v72
	v_add_f32_e32 v73, 1.0, v73
	v_add_f32_e32 v74, 1.0, v74
	v_rcp_f32_e32 v67, v67
	v_rcp_f32_e32 v72, v72
	v_rcp_f32_e32 v73, v73
	v_rcp_f32_e32 v74, v74
	v_cvt_pk_bf16_f32 v72, v67, v72
	v_mul_f32_e32 v67, 0xbfb8aa3b, v18
	v_cvt_pk_bf16_f32 v73, v73, v74
	global_store_dwordx2 v[70:71], v[72:73], off offset:64
	v_mul_f32_e32 v72, 0xbfb8aa3b, v19
	v_exp_f32_e32 v67, v67
	v_exp_f32_e32 v72, v72
	v_mul_f32_e32 v73, 0xbfb8aa3b, v20
	v_mul_f32_e32 v74, 0xbfb8aa3b, v21
	v_exp_f32_e32 v73, v73
	v_exp_f32_e32 v74, v74
	v_add_f32_e32 v67, 1.0, v67
	v_add_f32_e32 v72, 1.0, v72
	v_rcp_f32_e32 v67, v67
	v_rcp_f32_e32 v72, v72
	v_add_f32_e32 v73, 1.0, v73
	v_add_f32_e32 v74, 1.0, v74
	v_rcp_f32_e32 v73, v73
	v_rcp_f32_e32 v74, v74
	v_cvt_pk_bf16_f32 v72, v67, v72
	v_ashrrev_i32_e32 v67, 31, v66
	v_lshlrev_b64 v[66:67], 12, v[66:67]
	v_cvt_pk_bf16_f32 v73, v73, v74
	v_lshl_add_u64 v[66:67], s[8:9], 0, v[66:67]
	global_store_dwordx2 v[70:71], v[72:73], off offset:96
	v_lshl_add_u64 v[66:67], v[66:67], 0, v[0:1]
	v_mul_f32_e32 v0, 0xbfb8aa3b, v14
	v_mul_f32_e32 v70, 0xbfb8aa3b, v15
	v_mul_f32_e32 v71, 0xbfb8aa3b, v16
	v_mul_f32_e32 v72, 0xbfb8aa3b, v17
	v_exp_f32_e32 v0, v0
	v_exp_f32_e32 v70, v70
	v_exp_f32_e32 v71, v71
	v_exp_f32_e32 v72, v72
	v_add_f32_e32 v0, 1.0, v0
	v_add_f32_e32 v70, 1.0, v70
	v_add_f32_e32 v71, 1.0, v71
	v_add_f32_e32 v72, 1.0, v72
	v_rcp_f32_e32 v0, v0
	v_rcp_f32_e32 v70, v70
	v_rcp_f32_e32 v71, v71
	v_rcp_f32_e32 v72, v72
	v_lshl_add_u64 v[68:69], v[66:67], 0, v[68:69]
	v_lshl_add_u64 v[66:67], v[68:69], 0, s[38:39]
	v_add_co_u32_e32 v68, vcc, s10, v68
	v_cvt_pk_bf16_f32 v70, v0, v70
	v_cvt_pk_bf16_f32 v71, v71, v72
	v_addc_co_u32_e32 v69, vcc, 0, v69, vcc
	global_store_dwordx2 v[68:69], v[70:71], off offset:2048
	v_mul_f32_e32 v0, 0xbfb8aa3b, v10
	v_mul_f32_e32 v68, 0xbfb8aa3b, v11
	v_mul_f32_e32 v69, 0xbfb8aa3b, v12
	v_mul_f32_e32 v70, 0xbfb8aa3b, v13
	v_exp_f32_e32 v0, v0
	v_exp_f32_e32 v68, v68
	v_exp_f32_e32 v69, v69
	v_exp_f32_e32 v70, v70
	v_add_f32_e32 v0, 1.0, v0
	v_add_f32_e32 v68, 1.0, v68
	v_add_f32_e32 v69, 1.0, v69
	v_add_f32_e32 v70, 1.0, v70
	v_rcp_f32_e32 v0, v0
	v_rcp_f32_e32 v68, v68
	v_rcp_f32_e32 v69, v69
	v_rcp_f32_e32 v70, v70
	s_mov_b64 s[8:9], 0
	v_cvt_pk_bf16_f32 v68, v0, v68
	v_mul_f32_e32 v0, 0xbfb8aa3b, v6
	v_cvt_pk_bf16_f32 v69, v69, v70
	global_store_dwordx2 v[66:67], v[68:69], off offset:32
	v_mul_f32_e32 v68, 0xbfb8aa3b, v7
	v_mul_f32_e32 v69, 0xbfb8aa3b, v8
	v_mul_f32_e32 v70, 0xbfb8aa3b, v9
	v_exp_f32_e32 v0, v0
	v_exp_f32_e32 v68, v68
	v_exp_f32_e32 v69, v69
	v_exp_f32_e32 v70, v70
	v_add_f32_e32 v0, 1.0, v0
	v_add_f32_e32 v68, 1.0, v68
	v_add_f32_e32 v69, 1.0, v69
	v_add_f32_e32 v70, 1.0, v70
	v_rcp_f32_e32 v0, v0
	v_rcp_f32_e32 v68, v68
	v_rcp_f32_e32 v69, v69
	v_rcp_f32_e32 v70, v70
	v_cvt_pk_bf16_f32 v68, v0, v68
	v_mul_f32_e32 v0, 0xbfb8aa3b, v2
	v_cvt_pk_bf16_f32 v69, v69, v70
	global_store_dwordx2 v[66:67], v[68:69], off offset:64
	v_mul_f32_e32 v68, 0xbfb8aa3b, v3
	v_mul_f32_e32 v69, 0xbfb8aa3b, v4
	v_mul_f32_e32 v70, 0xbfb8aa3b, v5
	v_exp_f32_e32 v0, v0
	v_exp_f32_e32 v68, v68
	v_exp_f32_e32 v69, v69
	v_exp_f32_e32 v70, v70
	v_add_f32_e32 v0, 1.0, v0
	v_add_f32_e32 v68, 1.0, v68
	v_add_f32_e32 v69, 1.0, v69
	v_add_f32_e32 v70, 1.0, v70
	v_rcp_f32_e32 v0, v0
	v_rcp_f32_e32 v68, v68
	v_rcp_f32_e32 v69, v69
	v_rcp_f32_e32 v70, v70
	v_cvt_pk_bf16_f32 v68, v0, v68
	v_cvt_pk_bf16_f32 v69, v69, v70
	global_store_dwordx2 v[66:67], v[68:69], off offset:96

.Lg2_b_item1:
	s_mul_i32 s11, s10, 0x2aab
	s_lshr_b32 s11, s11, 16
	s_mul_i32 s12, s11, 6
	s_sub_u32 s12, s10, s12
	s_mov_b32 s16, 0
	s_and_b32 s17, s14, 3
	s_mul_i32 s17, s17, 6
	s_add_u32 s12, s12, s17
	s_lshl_b32 s12, s12, 8
	s_add_u32 s12, s12, s16
	s_lshr_b32 s17, s14, 2
	s_mul_i32 s17, s17, 22
	s_lshl_b32 s11, s11, 1
	s_add_u32 s11, s11, s17
	s_lshl_b32 s16, s12, 11
	s_add_u32 s0, s24, s16
	s_addc_u32 s1, s25, 0
	s_lshl_b32 s16, s11, 18
	s_add_u32 s2, s40, s16
	s_addc_u32 s3, s41, 0
	s_mul_i32 s16, s12, 0x1600
	s_lshl_b32 s17, s11, 7
	s_add_u32 s16, s16, s17
	s_add_u32 s4, s26, s16
	s_addc_u32 s5, s27, 0
	s_add_u32 m0, s6, 0x0
	s_nop 0
	global_load_lds_dwordx4 v136, s[0:1]
	s_add_u32 m0, s6, 0x2000
	s_nop 0
	global_load_lds_dwordx4 v137, s[0:1]
	s_add_u32 m0, s6, 0x4000
	s_nop 0
	global_load_lds_dwordx4 v136, s[2:3]
	s_add_u32 m0, s6, 0x6000
	s_nop 0
	global_load_lds_dwordx4 v137, s[2:3]
	s_add_u32 s0, s0, 64
	s_addc_u32 s1, s1, 0
	s_add_u32 s2, s2, 64
	s_addc_u32 s3, s3, 0
	s_add_u32 m0, s6, 0x8000
	s_nop 0
	global_load_lds_dwordx4 v136, s[0:1]
	s_add_u32 m0, s6, 0xa000
	s_nop 0
	global_load_lds_dwordx4 v137, s[0:1]
	s_add_u32 m0, s6, 0xc000
	s_nop 0
	global_load_lds_dwordx4 v136, s[2:3]
	s_add_u32 m0, s6, 0xe000
	s_nop 0
	global_load_lds_dwordx4 v137, s[2:3]
	s_add_u32 s0, s0, 64
	s_addc_u32 s1, s1, 0
	s_add_u32 s2, s2, 64
	s_addc_u32 s3, s3, 0
	s_add_u32 m0, s6, 0x10000
	s_nop 0
	global_load_lds_dwordx4 v136, s[0:1]
	s_add_u32 m0, s6, 0x12000
	s_nop 0
	global_load_lds_dwordx4 v137, s[0:1]
	s_add_u32 m0, s6, 0x14000
	s_nop 0
	global_load_lds_dwordx4 v136, s[2:3]
	s_add_u32 m0, s6, 0x16000
	s_nop 0
	global_load_lds_dwordx4 v137, s[2:3]
	s_add_u32 s0, s0, 64
	s_addc_u32 s1, s1, 0
	s_add_u32 s2, s2, 64
	s_addc_u32 s3, s3, 0
	v_mov_b32_e32 v2, 0
	v_mov_b32_e32 v3, 0
	v_mov_b32_e32 v4, 0
	v_mov_b32_e32 v5, 0
	v_mov_b32_e32 v6, 0
	v_mov_b32_e32 v7, 0
	v_mov_b32_e32 v8, 0
	v_mov_b32_e32 v9, 0
	v_mov_b32_e32 v10, 0
	v_mov_b32_e32 v11, 0
	v_mov_b32_e32 v12, 0
	v_mov_b32_e32 v13, 0
	v_mov_b32_e32 v14, 0
	v_mov_b32_e32 v15, 0
	v_mov_b32_e32 v16, 0
	v_mov_b32_e32 v17, 0
	v_mov_b32_e32 v18, 0
	v_mov_b32_e32 v19, 0
	v_mov_b32_e32 v20, 0
	v_mov_b32_e32 v21, 0
	v_mov_b32_e32 v22, 0
	v_mov_b32_e32 v23, 0
	v_mov_b32_e32 v24, 0
	v_mov_b32_e32 v25, 0
	v_mov_b32_e32 v26, 0
	v_mov_b32_e32 v27, 0
	v_mov_b32_e32 v28, 0
	v_mov_b32_e32 v29, 0
	v_mov_b32_e32 v30, 0
	v_mov_b32_e32 v31, 0
	v_mov_b32_e32 v32, 0
	v_mov_b32_e32 v33, 0
	v_mov_b32_e32 v34, 0
	v_mov_b32_e32 v35, 0
	v_mov_b32_e32 v36, 0
	v_mov_b32_e32 v37, 0
	v_mov_b32_e32 v38, 0
	v_mov_b32_e32 v39, 0
	v_mov_b32_e32 v40, 0
	v_mov_b32_e32 v41, 0
	v_mov_b32_e32 v42, 0
	v_mov_b32_e32 v43, 0
	v_mov_b32_e32 v44, 0
	v_mov_b32_e32 v45, 0
	v_mov_b32_e32 v46, 0
	v_mov_b32_e32 v47, 0
	v_mov_b32_e32 v48, 0
	v_mov_b32_e32 v49, 0
	v_mov_b32_e32 v50, 0
	v_mov_b32_e32 v51, 0
	v_mov_b32_e32 v52, 0
	v_mov_b32_e32 v53, 0
	v_mov_b32_e32 v54, 0
	v_mov_b32_e32 v55, 0
	v_mov_b32_e32 v56, 0
	v_mov_b32_e32 v57, 0
	v_mov_b32_e32 v58, 0
	v_mov_b32_e32 v59, 0
	v_mov_b32_e32 v60, 0
	v_mov_b32_e32 v61, 0
	v_mov_b32_e32 v62, 0
	v_mov_b32_e32 v63, 0
	v_mov_b32_e32 v64, 0
	v_mov_b32_e32 v65, 0
	v_mov_b32_e32 v66, 0
	v_mov_b32_e32 v67, 0
	v_mov_b32_e32 v68, 0
	v_mov_b32_e32 v69, 0
	v_mov_b32_e32 v70, 0
	v_mov_b32_e32 v71, 0
	v_mov_b32_e32 v72, 0
	v_mov_b32_e32 v73, 0
	v_mov_b32_e32 v74, 0
	v_mov_b32_e32 v75, 0
	v_mov_b32_e32 v76, 0
	v_mov_b32_e32 v77, 0
	v_mov_b32_e32 v78, 0
	v_mov_b32_e32 v79, 0
	v_mov_b32_e32 v80, 0
	v_mov_b32_e32 v81, 0
	v_mov_b32_e32 v82, 0
	v_mov_b32_e32 v83, 0
	v_mov_b32_e32 v84, 0
	v_mov_b32_e32 v85, 0
	v_mov_b32_e32 v86, 0
	v_mov_b32_e32 v87, 0
	v_mov_b32_e32 v88, 0
	v_mov_b32_e32 v89, 0
	v_mov_b32_e32 v90, 0
	v_mov_b32_e32 v91, 0
	v_mov_b32_e32 v92, 0
	v_mov_b32_e32 v93, 0
	v_mov_b32_e32 v94, 0
	v_mov_b32_e32 v95, 0
	v_mov_b32_e32 v96, 0
	v_mov_b32_e32 v97, 0
	v_mov_b32_e32 v98, 0
	v_mov_b32_e32 v99, 0
	v_mov_b32_e32 v100, 0
	v_mov_b32_e32 v101, 0
	v_mov_b32_e32 v102, 0
	v_mov_b32_e32 v103, 0
	v_mov_b32_e32 v104, 0
	v_mov_b32_e32 v105, 0
	v_mov_b32_e32 v106, 0
	v_mov_b32_e32 v107, 0
	v_mov_b32_e32 v108, 0
	v_mov_b32_e32 v109, 0
	v_mov_b32_e32 v110, 0
	v_mov_b32_e32 v111, 0
	v_mov_b32_e32 v112, 0
	v_mov_b32_e32 v113, 0
	v_mov_b32_e32 v114, 0
	v_mov_b32_e32 v115, 0
	v_mov_b32_e32 v116, 0
	v_mov_b32_e32 v117, 0
	v_mov_b32_e32 v118, 0
	v_mov_b32_e32 v119, 0
	v_mov_b32_e32 v120, 0
	v_mov_b32_e32 v121, 0
	v_mov_b32_e32 v122, 0
	v_mov_b32_e32 v123, 0
	v_mov_b32_e32 v124, 0
	v_mov_b32_e32 v125, 0
	v_mov_b32_e32 v126, 0
	v_mov_b32_e32 v127, 0
	v_mov_b32_e32 v128, 0
	v_mov_b32_e32 v129, 0
.Lg2_b_grpB2:
	v_mov_b32_e32 v178, 0
	v_mov_b32_e32 v179, 0
	v_mov_b32_e32 v180, 0
	v_mov_b32_e32 v181, 0
	v_mov_b32_e32 v182, 0
	v_mov_b32_e32 v183, 0
	v_mov_b32_e32 v184, 0
	v_mov_b32_e32 v185, 0
	v_mov_b32_e32 v186, 0
	v_mov_b32_e32 v187, 0
	v_mov_b32_e32 v188, 0
	v_mov_b32_e32 v189, 0
	v_mov_b32_e32 v190, 0
	v_mov_b32_e32 v191, 0
	v_mov_b32_e32 v192, 0
	v_mov_b32_e32 v193, 0
	v_mov_b32_e32 v218, 0
	v_mov_b32_e32 v219, 0
	v_mov_b32_e32 v220, 0
	v_mov_b32_e32 v221, 0
	v_mov_b32_e32 v222, 0
	v_mov_b32_e32 v223, 0
	v_mov_b32_e32 v224, 0
	v_mov_b32_e32 v225, 0
	v_mov_b32_e32 v226, 0
	v_mov_b32_e32 v227, 0
	v_mov_b32_e32 v228, 0
	v_mov_b32_e32 v229, 0
	v_mov_b32_e32 v230, 0
	v_mov_b32_e32 v231, 0
	v_mov_b32_e32 v232, 0
	v_mov_b32_e32 v233, 0
	s_mov_b32 s7, 7
